# g2 + attention work queues: next-item atomic issued at the end of the K/V tile loop (hidden under last tile/combine/stores)
# baseline (speedup 1.0000x reference)
; __device__ __forceinline__ int opaque_tid() { int t = threadIdx.x; asm volatile("" : "+v"(t)); return t; }
; template <int DK, int MODE, bool OUTF32> ...
;     ...
;     { auto rr = __builtin_amdgcn_permlane32_swap(__float_as_uint(l), __float_as_uint(l), false, false); l = __uint_as_float(rr[0]) + __uint_as_float(rr[1]); }
;     float* xo = (float*)a_lds + wave * 2176;
;     if (kh == 0) {
; #pragma unroll
;         for (int r = 0; r < 16; ++r) { xo[r * 64 + lane] = o[2][r]; xo[(16 + r) * 64 + lane] = o[3][r]; }
;     } else {
; #pragma unroll
;         for (int r = 0; r < 16; ++r) { xo[r * 64 + lane] = o[0][r]; xo[(16 + r) * 64 + lane] = o[1][r]; }
;     }
;     xo[2048 + lane] = m; xo[2112 + lane] = l;
;     __syncthreads();
;     const float* xp = (const float*)a_lds + (wave ^ 1) * 2176;
;     const float mp = xp[2048 + lane], lp = xp[2112 + lane];
;     const float M = fmaxf(m, mp), ea = __builtin_amdgcn_exp2f(m - M), eb = __builtin_amdgcn_exp2f(mp - M);
;     const float inv = 1.f / (l * ea + lp * eb), fa = ea * inv, fb = eb * inv;
;     ...
;     if (kh == 0) A_OUT(o[0], o[1], 0); else A_OUT(o[2], o[3], 2);
; template <bool NAIVE>
; __device__ __forceinline__ void attn_even_phase(const bf16_t* __restrict__ att, const float* __restrict__ cumh, const float* __restrict__ relb,
;                                                 bf16_t* __restrict__ Ob, unsigned* ctr, float* lds, const float* __restrict__ tot) {
;     ...
;             if (opaque_tid() == 0) *slot = NBLK + (int)atomicAdd(ctr, 1u);
.LBB0_266:
	s_or_b64 exec, exec, s[12:13]
	s_mov_b64 s[100:101], exec
	s_mov_b64 exec, -1
	v_cmp_eq_u32_e32 vcc, 0, v0
	s_mov_b64 exec, vcc
	v_mov_b64_e32 v[252:253], s[54:55]
	global_atomic_add v250, v[252:253], v198, off sc0
	s_mov_b64 exec, s[100:101]
	v_lshlrev_b32_e32 v2, 21, v194
	v_and_b32_e32 v2, 0x1000000, v2
	v_lshl_add_u64 v[68:69], s[52:53], 0, v[2:3]
	v_lshlrev_b32_e32 v2, 8, v195
	v_lshl_add_u64 v[70:71], v[68:69], 0, v[2:3]
	v_mov_b32_e32 v2, v210
	v_and_b32_e32 v72, 63, v182
	s_nop 0
	v_permlane32_swap_b32_e32 v210, v2
	s_movk_i32 s12, 0x2200
	v_add_f32_e32 v68, v210, v2
	v_mul_lo_u32 v2, v183, s12
	v_cmp_eq_u32_e32 vcc, 0, v185
	v_lshlrev_b32_e32 v69, 2, v72
	v_add3_u32 v2, 0, v2, v69
	v_cndmask_b32_e32 v86, v37, v53, vcc
	v_cndmask_b32_e32 v87, v36, v52, vcc
	v_cndmask_b32_e32 v72, v51, v67, vcc
	v_cndmask_b32_e32 v73, v50, v66, vcc
	v_cndmask_b32_e32 v74, v49, v65, vcc
	v_cndmask_b32_e32 v75, v48, v64, vcc
	v_cndmask_b32_e32 v76, v47, v63, vcc
	v_cndmask_b32_e32 v77, v46, v62, vcc
	v_cndmask_b32_e32 v78, v45, v61, vcc
	v_cndmask_b32_e32 v79, v44, v60, vcc
	v_cndmask_b32_e32 v80, v43, v59, vcc
	v_cndmask_b32_e32 v81, v42, v58, vcc
	v_cndmask_b32_e32 v82, v41, v57, vcc
	v_cndmask_b32_e32 v83, v40, v56, vcc
	v_cndmask_b32_e32 v84, v39, v55, vcc
	v_cndmask_b32_e32 v85, v38, v54, vcc
	v_cndmask_b32_e32 v88, v35, v19, vcc
	v_cndmask_b32_e32 v89, v34, v18, vcc
	v_cndmask_b32_e32 v90, v33, v17, vcc
	v_cndmask_b32_e32 v91, v32, v16, vcc
	v_cndmask_b32_e32 v92, v31, v15, vcc
	v_cndmask_b32_e32 v93, v30, v14, vcc
	v_cndmask_b32_e32 v94, v29, v13, vcc
	v_cndmask_b32_e32 v95, v28, v12, vcc
	v_cndmask_b32_e32 v96, v27, v11, vcc
	v_cndmask_b32_e32 v97, v26, v10, vcc
	v_cndmask_b32_e32 v98, v25, v9, vcc
	v_cndmask_b32_e32 v99, v24, v8, vcc
	v_cndmask_b32_e32 v100, v23, v7, vcc
	v_cndmask_b32_e32 v101, v22, v6, vcc
	v_cndmask_b32_e32 v102, v21, v5, vcc
	v_cndmask_b32_e32 v103, v20, v4, vcc
	ds_write2st64_b32 v2, v87, v86 offset1:1
	ds_write2st64_b32 v2, v103, v102 offset0:16 offset1:17
	ds_write2st64_b32 v2, v85, v84 offset0:2 offset1:3
	ds_write2st64_b32 v2, v101, v100 offset0:18 offset1:19
	ds_write2st64_b32 v2, v83, v82 offset0:4 offset1:5
	ds_write2st64_b32 v2, v99, v98 offset0:20 offset1:21
	ds_write2st64_b32 v2, v81, v80 offset0:6 offset1:7
	ds_write2st64_b32 v2, v97, v96 offset0:22 offset1:23
	ds_write2st64_b32 v2, v79, v78 offset0:8 offset1:9
	ds_write2st64_b32 v2, v95, v94 offset0:24 offset1:25
	ds_write2st64_b32 v2, v77, v76 offset0:10 offset1:11
	ds_write2st64_b32 v2, v93, v92 offset0:26 offset1:27
	ds_write2st64_b32 v2, v75, v74 offset0:12 offset1:13
	ds_write2st64_b32 v2, v91, v90 offset0:28 offset1:29
	ds_write2st64_b32 v2, v73, v72 offset0:14 offset1:15
	ds_write2st64_b32 v2, v89, v88 offset0:30 offset1:31
	ds_write2st64_b32 v2, v223, v68 offset0:32 offset1:33
	v_xor_b32_e32 v2, 1, v183
	v_mul_lo_u32 v2, v2, s12
	v_add3_u32 v86, 0, v2, v69
	s_waitcnt lgkmcnt(0)
	s_barrier
	ds_read2st64_b32 v[72:73], v86 offset0:32 offset1:33
	v_max_f32_e32 v69, v223, v223
	v_cmp_ne_u32_e64 s[40:41], 0, v185
	s_waitcnt lgkmcnt(0)
	v_max_f32_e32 v2, v72, v72
	v_max_f32_e32 v2, v69, v2
	v_sub_f32_e32 v69, v223, v2
	v_sub_f32_e32 v2, v72, v2
	v_exp_f32_e32 v74, v69
	v_exp_f32_e32 v75, v2
	v_mov_b32_e32 v69, v73
	v_pk_mul_f32 v[68:69], v[68:69], v[74:75]
	s_nop 0
	v_add_f32_e32 v2, v68, v69
	v_div_scale_f32 v68, s[12:13], v2, v2, 1.0
	v_rcp_f32_e32 v69, v68
	s_nop 0
	v_fma_f32 v72, -v68, v69, 1.0
	v_fmac_f32_e32 v69, v72, v69
	v_div_scale_f32 v72, vcc, 1.0, v2, 1.0
	v_mul_f32_e32 v73, v72, v69
	v_fma_f32 v76, -v68, v73, v72
	v_fmac_f32_e32 v73, v76, v69
	v_fma_f32 v68, -v68, v73, v72
	v_div_fmas_f32 v68, v68, v69, v73
	v_div_fixup_f32 v2, v68, v2, 1.0
	v_mov_b32_e32 v68, v75
	v_mov_b32_e32 v69, v74
	ds_read2st64_b32 v[74:75], v86 offset1:1
	v_pk_mul_f32 v[68:69], v[68:69], v[2:3] op_sel_hi:[1,0]
	v_lshlrev_b64 v[72:73], 12, v[180:181]
	v_lshl_add_u64 v[72:73], v[70:71], 0, v[72:73]
	v_mov_b32_e32 v2, v1
	s_waitcnt lgkmcnt(0)
	v_pk_mul_f32 v[78:79], v[74:75], v[68:69] op_sel_hi:[1,0]
	ds_read2st64_b32 v[74:75], v86 offset0:2 offset1:3
	v_mov_b32_e32 v70, v68
	v_mov_b32_e32 v71, v68
	s_waitcnt lgkmcnt(0)
	v_pk_mul_f32 v[84:85], v[74:75], v[68:69] op_sel_hi:[1,0]
	v_lshl_add_u64 v[74:75], v[2:3], 1, v[72:73]
	s_and_saveexec_b64 s[12:13], s[40:41]
	s_xor_b64 s[40:41], exec, s[12:13]
	s_cbranch_execz .LBB0_268
	v_pk_fma_f32 v[20:21], v[52:53], v[68:69], v[78:79] op_sel:[0,1,0]
	v_pk_fma_f32 v[22:23], v[54:55], v[68:69], v[84:85] op_sel:[0,1,0]
	v_cvt_pk_bf16_f32 v20, v20, v21
	v_cvt_pk_bf16_f32 v21, v22, v23
	ds_read2st64_b32 v[22:23], v86 offset0:4 offset1:5
	global_store_dwordx2 v[74:75], v[20:21], off offset:2176
	ds_read2st64_b32 v[20:21], v86 offset0:6 offset1:7
	ds_read2st64_b32 v[24:25], v86 offset0:8 offset1:9
	ds_read2st64_b32 v[26:27], v86 offset0:10 offset1:11
	s_mov_b64 s[12:13], 0x8c0
	v_lshl_add_u64 v[82:83], v[74:75], 0, s[12:13]
	s_waitcnt lgkmcnt(3)
	v_pk_mul_f32 v[22:23], v[70:71], v[22:23]
	s_waitcnt lgkmcnt(2)
	v_pk_mul_f32 v[20:21], v[70:71], v[20:21]
	v_pk_fma_f32 v[22:23], v[56:57], v[68:69], v[22:23] op_sel:[0,1,0]
	v_pk_fma_f32 v[20:21], v[58:59], v[68:69], v[20:21] op_sel:[0,1,0]
	v_cvt_pk_bf16_f32 v22, v22, v23
	v_cvt_pk_bf16_f32 v23, v20, v21
	global_store_dwordx2 v[74:75], v[22:23], off offset:2192
	s_waitcnt lgkmcnt(1)
	v_pk_mul_f32 v[20:21], v[70:71], v[24:25]
	s_waitcnt lgkmcnt(0)
	v_pk_mul_f32 v[22:23], v[70:71], v[26:27]
	v_pk_fma_f32 v[20:21], v[60:61], v[68:69], v[20:21] op_sel:[0,1,0]
	v_pk_fma_f32 v[22:23], v[62:63], v[68:69], v[22:23] op_sel:[0,1,0]
	v_cvt_pk_bf16_f32 v20, v20, v21
	v_cvt_pk_bf16_f32 v21, v22, v23
	ds_read2st64_b32 v[22:23], v86 offset0:12 offset1:13
	global_store_dwordx2 v[74:75], v[20:21], off offset:2208
	ds_read2st64_b32 v[20:21], v86 offset0:14 offset1:15
	ds_read2st64_b32 v[24:25], v86 offset0:16 offset1:17
	ds_read2st64_b32 v[26:27], v86 offset0:18 offset1:19
	v_mov_b32_e32 v77, v69
	v_mov_b32_e32 v76, v69
	s_waitcnt lgkmcnt(3)
	v_pk_mul_f32 v[22:23], v[70:71], v[22:23]
	s_waitcnt lgkmcnt(2)
	v_pk_mul_f32 v[20:21], v[70:71], v[20:21]
	v_pk_fma_f32 v[22:23], v[64:65], v[68:69], v[22:23] op_sel:[0,1,0]
	v_pk_fma_f32 v[20:21], v[66:67], v[68:69], v[20:21] op_sel:[0,1,0]
	v_cvt_pk_bf16_f32 v22, v22, v23
	v_cvt_pk_bf16_f32 v23, v20, v21
	s_waitcnt lgkmcnt(1)
	v_pk_mul_f32 v[20:21], v[70:71], v[24:25]
	global_store_dwordx2 v[74:75], v[22:23], off offset:2224
	v_pk_fma_f32 v[4:5], v[4:5], v[68:69], v[20:21] op_sel:[0,1,0]
	s_waitcnt lgkmcnt(0)
	v_pk_mul_f32 v[20:21], v[70:71], v[26:27]
	v_cvt_pk_bf16_f32 v80, v4, v5
	v_pk_fma_f32 v[6:7], v[6:7], v[68:69], v[20:21] op_sel:[0,1,0]
	v_mov_b32_e32 v32, v16
	v_cvt_pk_bf16_f32 v81, v6, v7

; __device__ __forceinline__ int opaque_tid() { int t = threadIdx.x; asm volatile("" : "+v"(t)); return t; }
; template <int DK, int MODE, bool OUTF32> ...
;     ...
;             for (int s = 0; s < NKS; ++s) p = __builtin_amdgcn_mfma_f32_32x32x16_bf16(HOISTK ? kf[s] : *(const bf16x8*)(kb + s * 32), qf[s], p, 0, 0, 0);
;             if (HOISTV) { A_VREADS(3, 4); __builtin_amdgcn_sched_barrier(0); }
;             if (MODE == 0) {
;                 const float* ckp = (const float*)(a_lds + OFF_CK + cur * 256) + 32 * kh + 4 * hi;
; #pragma unroll
;                 for (int g = 0; g < 4; ++g) {
;                     const float4 ck = *(const float4*)(ckp + 8 * g);
;                     p[4 * g + 0] = fmaf(p[4 * g + 0], sc2, cq - ck.x); p[4 * g + 1] = fmaf(p[4 * g + 1], sc2, cq - ck.y);
;                     p[4 * g + 2] = fmaf(p[4 * g + 2], sc2, cq - ck.z); p[4 * g + 3] = fmaf(p[4 * g + 3], sc2, cq - ck.w);
;                 }
;                 if (64 * t + 32 * kh + 31 > qw0) {
;                     const int kbase = 64 * t + 32 * kh + 4 * hi;
; #pragma unroll
;                     for (int r = 0; r < 16; ++r) if (kbase + (r & 3) + 8 * (r >> 2) > qrow) p[r] = NEGINF;
;                 }
; template <bool NAIVE>
; __device__ __forceinline__ void attn_even_phase(const bf16_t* __restrict__ att, const float* __restrict__ cumh, const float* __restrict__ relb,
;                                                 bf16_t* __restrict__ Ob, unsigned* ctr, float* lds, const float* __restrict__ tot) {
;     ...
;             if (opaque_tid() == 0) *slot = NBLK + (int)atomicAdd(ctr, 1u);
.LBB0_290:
	s_or_b64 exec, exec, s[44:45]
	s_mov_b64 s[100:101], exec
	s_mov_b64 exec, -1
	v_cmp_eq_u32_e32 vcc, 0, v0
	s_mov_b64 exec, vcc
	v_mov_b64_e32 v[252:253], s[54:55]
	global_atomic_add v250, v[252:253], v198, off sc0
	s_mov_b64 exec, s[100:101]
	s_movk_i32 s12, 0xffc0
	v_and_or_b32 v2, v178, s12, v181
	v_cmp_le_i32_e32 vcc, v2, v182
	s_and_saveexec_b64 s[40:41], vcc
	s_cbranch_execz .LBB0_296
	ds_read_b128 v[84:87], v177 offset:17408
	ds_read_b128 v[132:135], v177 offset:17440
	ds_read_b128 v[136:139], v177 offset:17472
	ds_read_b128 v[140:143], v177 offset:17504
	ds_read_b128 v[144:147], v177 offset:17536
	ds_read_b128 v[148:151], v177 offset:17568
	ds_read_b128 v[160:163], v177 offset:17600
	ds_read_b128 v[164:167], v177 offset:17632
	s_waitcnt lgkmcnt(7)
	v_mfma_f32_32x32x16_bf16 v[84:99], v[84:87], v[128:131], 0
	s_waitcnt lgkmcnt(6)
	v_mfma_f32_32x32x16_bf16 v[84:99], v[132:135], v[124:127], v[84:99]
	s_waitcnt lgkmcnt(5)
	v_mfma_f32_32x32x16_bf16 v[84:99], v[136:139], v[120:123], v[84:99]
	s_waitcnt lgkmcnt(4)
	v_mfma_f32_32x32x16_bf16 v[84:99], v[140:143], v[112:115], v[84:99]
	s_waitcnt lgkmcnt(3)
	v_mfma_f32_32x32x16_bf16 v[84:99], v[144:147], v[116:119], v[84:99]
	ds_read_b128 v[112:115], v173 offset:256
	ds_read_b128 v[116:119], v173 offset:288
	s_waitcnt lgkmcnt(1)
	v_sub_f32_e32 v121, v77, v115
	v_sub_f32_e32 v120, v78, v114
	s_waitcnt lgkmcnt(0)
	v_sub_f32_e32 v123, v75, v117
	v_mfma_f32_32x32x16_bf16 v[84:99], v[148:151], v[108:111], v[84:99]
	v_sub_f32_e32 v122, v76, v116
	ds_read_b128 v[114:117], v173 offset:320
	ds_read_b128 v[108:111], v173 offset:352
	v_sub_f32_e32 v77, v73, v119
	v_sub_f32_e32 v76, v70, v118
	v_sub_f32_e32 v68, v68, v112
	s_waitcnt lgkmcnt(1)
	v_sub_f32_e32 v115, v69, v115
	v_mfma_f32_32x32x16_bf16 v[84:99], v[160:163], v[104:107], v[84:99]
	v_sub_f32_e32 v114, v72, v114
	v_sub_f32_e32 v73, v71, v117
	v_sub_f32_e32 v72, v74, v116
	s_waitcnt lgkmcnt(0)
	v_sub_f32_e32 v71, v79, v109
	v_sub_f32_e32 v70, v80, v108
	v_sub_f32_e32 v75, v81, v111
	v_sub_f32_e32 v74, v82, v110
	v_mfma_f32_32x32x16_bf16 v[84:99], v[164:167], v[100:103], v[84:99]
	v_sub_f32_e32 v69, v1, v113
	v_or_b32_e32 v1, 31, v2
	v_cmp_gt_i32_e32 vcc, v1, v159
	s_nop 8
	v_pk_fma_f32 v[80:81], v[84:85], s[24:25], v[68:69] op_sel_hi:[1,0,1]
	v_pk_fma_f32 v[68:69], v[98:99], s[24:25], v[74:75] op_sel_hi:[1,0,1]
	v_pk_fma_f32 v[70:71], v[96:97], s[24:25], v[70:71] op_sel_hi:[1,0,1]
	v_pk_fma_f32 v[72:73], v[94:95], s[24:25], v[72:73] op_sel_hi:[1,0,1]
	v_pk_fma_f32 v[74:75], v[92:93], s[24:25], v[114:115] op_sel_hi:[1,0,1]
	v_pk_fma_f32 v[76:77], v[90:91], s[24:25], v[76:77] op_sel_hi:[1,0,1]
	v_pk_fma_f32 v[78:79], v[88:89], s[24:25], v[122:123] op_sel_hi:[1,0,1]
	v_pk_fma_f32 v[82:83], v[86:87], s[24:25], v[120:121] op_sel_hi:[1,0,1]
	s_and_saveexec_b64 s[12:13], vcc
	s_cbranch_execz .LBB0_293
	v_or_b32_e32 v1, v2, v152
	v_cmp_lt_i32_e32 vcc, v1, v154
	v_or_b32_e32 v2, 2, v1
	s_nop 0
	v_cndmask_b32_e32 v81, v206, v81, vcc
	v_cmp_le_i32_e32 vcc, v1, v154
	s_nop 1
	v_cndmask_b32_e32 v80, v206, v80, vcc
	v_cmp_le_i32_e32 vcc, v2, v154
	v_or_b32_e32 v2, 3, v1
	s_nop 0
	v_cndmask_b32_e32 v82, v206, v82, vcc
	v_cmp_le_i32_e32 vcc, v2, v154
	v_or_b32_e32 v2, 8, v1
	s_nop 0
	v_cndmask_b32_e32 v83, v206, v83, vcc
	v_cmp_le_i32_e32 vcc, v2, v154
	v_or_b32_e32 v2, 9, v1
	s_nop 0
	v_cndmask_b32_e32 v78, v206, v78, vcc
	v_cmp_le_i32_e32 vcc, v2, v154
	v_or_b32_e32 v2, 10, v1
	s_nop 0
	v_cndmask_b32_e32 v79, v206, v79, vcc
	v_cmp_le_i32_e32 vcc, v2, v154
	v_or_b32_e32 v2, 11, v1
	s_nop 0
	v_cndmask_b32_e32 v76, v206, v76, vcc
	v_cmp_le_i32_e32 vcc, v2, v154
	v_or_b32_e32 v2, 16, v1
	s_nop 0
	v_cndmask_b32_e32 v77, v206, v77, vcc
	v_cmp_le_i32_e32 vcc, v2, v154
	v_or_b32_e32 v2, 17, v1
	s_nop 0
	v_cndmask_b32_e32 v74, v206, v74, vcc
	v_cmp_le_i32_e32 vcc, v2, v154
	v_or_b32_e32 v2, 18, v1
	s_nop 0
	v_cndmask_b32_e32 v75, v206, v75, vcc
	v_cmp_le_i32_e32 vcc, v2, v154
	v_or_b32_e32 v2, 19, v1
	s_nop 0
	v_cndmask_b32_e32 v72, v206, v72, vcc
	v_cmp_le_i32_e32 vcc, v2, v154
	v_or_b32_e32 v2, 24, v1
	s_nop 0
	v_cndmask_b32_e32 v73, v206, v73, vcc
	v_cmp_le_i32_e32 vcc, v2, v154
	v_or_b32_e32 v2, 25, v1
	s_nop 0
	v_cndmask_b32_e32 v70, v206, v70, vcc
	v_cmp_le_i32_e32 vcc, v2, v154
	v_or_b32_e32 v2, 26, v1
	v_or_b32_e32 v1, 27, v1
	v_cndmask_b32_e32 v71, v206, v71, vcc
	v_cmp_le_i32_e32 vcc, v2, v154
	s_nop 1
	v_cndmask_b32_e32 v68, v206, v68, vcc
	v_cmp_le_i32_e32 vcc, v1, v154
	s_nop 1
	v_cndmask_b32_e32 v69, v206, v69, vcc

; __device__ __forceinline__ int opaque_tid() { int t = threadIdx.x; asm volatile("" : "+v"(t)); return t; }
; template <bool NAIVE>
; __device__ __forceinline__ void attn_even_phase(const bf16_t* __restrict__ att, const float* __restrict__ cumh, const float* __restrict__ relb,
;                                                 bf16_t* __restrict__ Ob, unsigned* ctr, float* lds, const float* __restrict__ tot) {
;     ...
;             if (opaque_tid() == 0) *slot = NBLK + (int)atomicAdd(ctr, 1u);
;             __syncthreads();
;             item = *slot;
.LBB0_301:
	s_or_b64 exec, exec, s[42:43]
	v_mov_b32_e32 v1, v0
	s_waitcnt lgkmcnt(0)
	s_nop 0
	v_cmp_eq_u32_e32 vcc, 0, v1
	s_and_saveexec_b64 s[12:13], vcc
	s_cbranch_execz .LBB0_238
	v_mov_b64_e32 v[4:5], s[54:55]
	s_mov_b64 s[14:15], src_shared_base
	s_add_i32 s14, 0, 0x23000
	s_cmp_lg_u32 s14, -1
	s_cselect_b32 s14, s14, 0
	s_cselect_b32 s15, s15, 0
	v_mov_b32_e32 v4, s14
	v_mov_b32_e32 v5, s15
	s_waitcnt vmcnt(0) lgkmcnt(0)
	v_add_u32_e32 v1, 0x100, v250
	flat_store_dword v[4:5], v1 sc0 sc1
	s_waitcnt vmcnt(0)
	s_branch .LBB0_238

; template <int DK, int MODE, bool OUTF32> ...
;     ...
;     for (int t = t_lo; t < t_hi; ++t) {
;         const int cur = (t - t_lo) & 1;
;         if (t + 1 < t_hi) A_ISSUE(t + 1);
;         bool act;
;         if (MODE == 0) act = (64 * t + 32 * kh) <= (qw0 + 31);
;         else if (MODE == 1) act = (t <= cw) && (t >= cw - 8);
;         else act = (t <= cw);
;         if (act) {
;             f32x16 p;
; #pragma unroll
;             for (int r = 0; r < 16; ++r) p[r] = 0.f;
;             const unsigned char* kb = a_lds + cur * KBUF + (32 * kh + c) * KP + hi * 16;
;             constexpr bool HOISTK = true;
;             bf16x8 kf[NKS];
;             if (HOISTK) {
; #pragma unroll
;                 for (int s = 0; s < NKS; ++s) kf[s] = *(const bf16x8*)(kb + s * 32);
;             }
;             const unsigned char* vb = a_lds + OFF_V + cur * VBUF + c * VP + (32 * kh + 4 * hi) * 2;
;             bf16x8 vf[8];
;     ...
;             constexpr bool HOISTV = (DK == 128) && (MODE == 2 || MODE == 1);
;             if (HOISTV) A_VREADS(0, 3);
;             if (HOISTK) __builtin_amdgcn_sched_barrier(0);
; #pragma unroll
;             for (int s = 0; s < NKS; ++s) p = __builtin_amdgcn_mfma_f32_32x32x16_bf16(HOISTK ? kf[s] : *(const bf16x8*)(kb + s * 32), qf[s], p, 0, 0, 0);
;             if (HOISTV) { A_VREADS(3, 4); __builtin_amdgcn_sched_barrier(0); }
;             if (MODE == 0) {
;                 const float* ckp = (const float*)(a_lds + OFF_CK + cur * 256) + 32 * kh + 4 * hi;
; #pragma unroll
;                 for (int g = 0; g < 4; ++g) {
;                     const float4 ck = *(const float4*)(ckp + 8 * g);
;                     p[4 * g + 0] = fmaf(p[4 * g + 0], sc2, cq - ck.x); p[4 * g + 1] = fmaf(p[4 * g + 1], sc2, cq - ck.y);
;                     p[4 * g + 2] = fmaf(p[4 * g + 2], sc2, cq - ck.z); p[4 * g + 3] = fmaf(p[4 * g + 3], sc2, cq - ck.w);
;                 }
;                 if (64 * t + 32 * kh + 31 > qw0) {
;                     const int kbase = 64 * t + 32 * kh + 4 * hi;
; #pragma unroll
;                     for (int r = 0; r < 16; ++r) if (kbase + (r & 3) + 8 * (r >> 2) > qrow) p[r] = NEGINF;
;                 }
; __device__ __forceinline__ void attn_odd_phase(const bf16_t* __restrict__ att, bf16_t* __restrict__ Ob, float* __restrict__ A12, unsigned* ctr) {
;     ...
;         if (opaque_tid() == 0) *slot = NBLK + (int)atomicAdd(ctr, 1u);
.LBB0_946:
	s_or_b64 exec, exec, s[42:43]
	s_mov_b64 s[100:101], exec
	s_mov_b64 exec, -1
	v_cmp_eq_u32_e32 vcc, 0, v0
	s_mov_b64 exec, vcc
	v_mov_b64_e32 v[252:253], s[48:49]
	global_atomic_add v250, v[252:253], v198, off sc0
	s_mov_b64 exec, s[100:101]
	v_cmp_lt_i32_e32 vcc, v1, v187
	s_and_saveexec_b64 s[42:43], vcc
	s_cbranch_execz .LBB0_950
	ds_read_b128 v[68:71], v183 offset:17408
	ds_read_b128 v[140:143], v183 offset:17440
	ds_read_b128 v[144:147], v183 offset:17472
	ds_read_b128 v[148:151], v183 offset:17504
	ds_read_b128 v[152:155], v183 offset:17536
	ds_read_b128 v[156:159], v183 offset:17568
	ds_read_b128 v[160:163], v183 offset:17600
	ds_read_b128 v[172:175], v183 offset:17632
	v_add_u32_e32 v1, 0xc800, v184
	v_add_u32_e32 v72, 0x4000, v1
	ds_read2_b64 v[116:119], v72 offset0:128 offset1:130
	ds_read2_b64 v[120:123], v72 offset0:132 offset1:134
	v_add_u32_e32 v72, 0x5000, v1
	ds_read2_b64 v[124:127], v72 offset0:160 offset1:162
	ds_read2_b64 v[128:131], v72 offset0:164 offset1:166
	v_add_u32_e32 v72, 0x6000, v1
	ds_read2_b64 v[132:135], v72 offset0:192 offset1:194
	ds_read2_b64 v[136:139], v72 offset0:196 offset1:198
	s_waitcnt lgkmcnt(13)
	v_mfma_f32_32x32x16_bf16 v[68:83], v[68:71], v[112:115], 0
	v_add_u32_e32 v1, 0x7000, v1
	s_waitcnt lgkmcnt(12)
	v_mfma_f32_32x32x16_bf16 v[68:83], v[140:143], v[108:111], v[68:83]
	s_waitcnt lgkmcnt(11)
	v_mfma_f32_32x32x16_bf16 v[68:83], v[144:147], v[104:107], v[68:83]
	s_waitcnt lgkmcnt(10)
	v_mfma_f32_32x32x16_bf16 v[68:83], v[148:151], v[100:103], v[68:83]
	s_waitcnt lgkmcnt(9)
	v_mfma_f32_32x32x16_bf16 v[68:83], v[152:155], v[96:99], v[68:83]
	s_waitcnt lgkmcnt(8)
	v_mfma_f32_32x32x16_bf16 v[68:83], v[156:159], v[92:95], v[68:83]
	s_waitcnt lgkmcnt(7)
	v_mfma_f32_32x32x16_bf16 v[68:83], v[160:163], v[88:91], v[68:83]
	ds_read2_b64 v[92:95], v1 offset0:224 offset1:226
	ds_read2_b64 v[88:91], v1 offset0:228 offset1:230
	s_waitcnt lgkmcnt(8)
	v_mfma_f32_32x32x16_bf16 v[68:83], v[172:175], v[84:87], v[68:83]
	s_nop 11
	v_max_f32_e32 v1, v69, v69
	v_max_f32_e32 v84, v68, v68
	v_max_f32_e32 v1, v84, v1
	v_max3_f32 v1, v1, v70, v71
	v_max3_f32 v1, v1, v72, v73
	v_max3_f32 v1, v1, v74, v75
	v_max3_f32 v1, v1, v76, v77
	v_max3_f32 v1, v1, v78, v79
	v_max3_f32 v1, v1, v80, v81
	v_max3_f32 v1, v1, v82, v83
	v_mul_f32_e32 v1, 0x3e0293ee, v1
	v_mov_b32_e32 v84, v1
	s_nop 1
	v_permlane32_swap_b32_e32 v1, v84
	v_max_f32_e32 v84, v84, v84
	v_max_f32_e32 v1, v1, v1
	v_max_f32_e32 v1, v1, v84
	v_sub_f32_e32 v84, v1, v181
	s_mov_b32 s12, 0x41000000
	v_cmp_ge_f32_e32 vcc, s12, v84
	s_cmp_eq_u64 vcc, exec
	s_cbranch_scc1 .LBB0_949
	v_max_f32_e32 v1, v1, v1
	v_max_f32_e32 v84, v181, v181
	v_max_f32_e32 v1, v84, v1
	v_sub_f32_e32 v84, v181, v1
	v_exp_f32_e32 v84, v84
	v_mov_b32_e32 v181, v1
	v_pk_mul_f32 v[66:67], v[66:67], v[84:85] op_sel_hi:[1,0]
	v_pk_mul_f32 v[64:65], v[64:65], v[84:85] op_sel_hi:[1,0]
	v_pk_mul_f32 v[62:63], v[62:63], v[84:85] op_sel_hi:[1,0]
	v_pk_mul_f32 v[60:61], v[60:61], v[84:85] op_sel_hi:[1,0]
	v_pk_mul_f32 v[58:59], v[58:59], v[84:85] op_sel_hi:[1,0]
	v_pk_mul_f32 v[56:57], v[56:57], v[84:85] op_sel_hi:[1,0]
	v_pk_mul_f32 v[54:55], v[54:55], v[84:85] op_sel_hi:[1,0]
	v_pk_mul_f32 v[52:53], v[52:53], v[84:85] op_sel_hi:[1,0]
	v_pk_mul_f32 v[34:35], v[34:35], v[84:85] op_sel_hi:[1,0]
	v_pk_mul_f32 v[32:33], v[32:33], v[84:85] op_sel_hi:[1,0]
	v_pk_mul_f32 v[30:31], v[30:31], v[84:85] op_sel_hi:[1,0]
	v_pk_mul_f32 v[28:29], v[28:29], v[84:85] op_sel_hi:[1,0]
	v_pk_mul_f32 v[26:27], v[26:27], v[84:85] op_sel_hi:[1,0]
	v_pk_mul_f32 v[24:25], v[24:25], v[84:85] op_sel_hi:[1,0]
	v_pk_mul_f32 v[22:23], v[22:23], v[84:85] op_sel_hi:[1,0]
	v_pk_mul_f32 v[20:21], v[20:21], v[84:85] op_sel_hi:[1,0]
	v_pk_mul_f32 v[50:51], v[50:51], v[84:85] op_sel_hi:[1,0]
	v_pk_mul_f32 v[48:49], v[48:49], v[84:85] op_sel_hi:[1,0]
	v_pk_mul_f32 v[46:47], v[46:47], v[84:85] op_sel_hi:[1,0]
	v_pk_mul_f32 v[44:45], v[44:45], v[84:85] op_sel_hi:[1,0]
	v_pk_mul_f32 v[42:43], v[42:43], v[84:85] op_sel_hi:[1,0]
	v_pk_mul_f32 v[40:41], v[40:41], v[84:85] op_sel_hi:[1,0]
	v_pk_mul_f32 v[38:39], v[38:39], v[84:85] op_sel_hi:[1,0]
	v_pk_mul_f32 v[36:37], v[36:37], v[84:85] op_sel_hi:[1,0]
	v_pk_mul_f32 v[18:19], v[18:19], v[84:85] op_sel_hi:[1,0]
	v_pk_mul_f32 v[16:17], v[16:17], v[84:85] op_sel_hi:[1,0]
	v_pk_mul_f32 v[14:15], v[14:15], v[84:85] op_sel_hi:[1,0]
	v_pk_mul_f32 v[12:13], v[12:13], v[84:85] op_sel_hi:[1,0]
	v_pk_mul_f32 v[10:11], v[10:11], v[84:85] op_sel_hi:[1,0]
	v_pk_mul_f32 v[8:9], v[8:9], v[84:85] op_sel_hi:[1,0]
	v_pk_mul_f32 v[6:7], v[6:7], v[84:85] op_sel_hi:[1,0]
	v_pk_mul_f32 v[4:5], v[4:5], v[84:85] op_sel_hi:[1,0]
	v_mul_f32_e32 v179, v179, v84

; template <int DK, int MODE, bool OUTF32> ...
;     ...
;             if (HOISTK) __builtin_amdgcn_sched_barrier(0);
; #pragma unroll
;             for (int s = 0; s < NKS; ++s) p = __builtin_amdgcn_mfma_f32_32x32x16_bf16(HOISTK ? kf[s] : *(const bf16x8*)(kb + s * 32), qf[s], p, 0, 0, 0);
;             if (HOISTV) { A_VREADS(3, 4); __builtin_amdgcn_sched_barrier(0); }
;             if (MODE == 0) {
;                 const float* ckp = (const float*)(a_lds + OFF_CK + cur * 256) + 32 * kh + 4 * hi;
; #pragma unroll
;                 for (int g = 0; g < 4; ++g) {
;                     const float4 ck = *(const float4*)(ckp + 8 * g);
;                     p[4 * g + 0] = fmaf(p[4 * g + 0], sc2, cq - ck.x); p[4 * g + 1] = fmaf(p[4 * g + 1], sc2, cq - ck.y);
;                     p[4 * g + 2] = fmaf(p[4 * g + 2], sc2, cq - ck.z); p[4 * g + 3] = fmaf(p[4 * g + 3], sc2, cq - ck.w);
;                 }
;                 if (64 * t + 32 * kh + 31 > qw0) {
;                     const int kbase = 64 * t + 32 * kh + 4 * hi;
; #pragma unroll
;                     for (int r = 0; r < 16; ++r) if (kbase + (r & 3) + 8 * (r >> 2) > qrow) p[r] = NEGINF;
;                 }
;             } else if (MODE == 1) {
;                 const float* rb = (const float*)(a_lds + OFF_RB);
;                 if (t <= cw - 3) {
;                     const float bb = rb[256];
; #pragma unroll
;                     for (int r = 0; r < 16; ++r) p[r] = fmaf(p[r], sc2, bb);
;                 } else {
;                     const int kbase = 64 * t + 32 * kh + 4 * hi;
; #pragma unroll
;                     for (int r = 0; r < 16; ++r) { int rel = qrow - (kbase + (r & 3) + 8 * (r >> 2)); rel = rel > 128 ? 128 : rel; p[r] = fmaf(p[r], sc2, rb[rel + 128]); }
;                 }
;             }
;             float mx = p[0];
; #pragma unroll
;             for (int r = 1; r < 16; ++r) mx = fmaxf(mx, p[r]);
;             if (MODE == 2) mx *= sc2;
;             { auto rr = __builtin_amdgcn_permlane32_swap(__float_as_uint(mx), __float_as_uint(mx), false, false); mx = fmaxf(__uint_as_float(rr[0]), __uint_as_float(rr[1])); }
;             if (!__all(mx - m <= 8.f)) {
;                 const float mn = fmaxf(m, mx), alpha = __builtin_amdgcn_exp2f(m - mn);
;                 m = mn; l *= alpha;
; #pragma unroll
;                 for (int db = 0; db < 4; ++db)
; #pragma unroll
.LBB0_962:
	s_or_b64 exec, exec, s[42:43]
	s_mov_b64 s[100:101], exec
	s_mov_b64 exec, -1
	v_cmp_eq_u32_e32 vcc, 0, v0
	s_mov_b64 exec, vcc
	v_mov_b64_e32 v[252:253], s[48:49]
	global_atomic_add v250, v[252:253], v198, off sc0
	s_mov_b64 exec, s[100:101]
	v_cmp_lt_i32_e32 vcc, v1, v179
	s_and_saveexec_b64 s[42:43], vcc
	s_cbranch_execz .LBB0_966
	ds_read_b128 v[4:7], v176 offset:25600
	ds_read_b128 v[8:11], v176 offset:25632
	ds_read_b128 v[12:15], v176 offset:25664
	ds_read_b128 v[146:149], v176 offset:25696
	ds_read_b128 v[150:153], v176 offset:25728
	ds_read_b128 v[162:165], v176 offset:25760
	ds_read_b128 v[166:169], v176 offset:25792
	ds_read_b128 v[178:181], v176 offset:25824
	ds_read_b128 v[182:185], v176 offset:25856
	ds_read_b128 v[186:189], v176 offset:25888
	ds_read_b128 v[190:193], v176 offset:25920
	ds_read_b128 v[194:197], v176 offset:25952
	s_waitcnt lgkmcnt(11)
	v_mfma_f32_32x32x16_bf16 v[82:97], v[4:7], v[142:145], 0
	s_mov_b32 s12, 0x41000000
	s_waitcnt lgkmcnt(10)
	v_mfma_f32_32x32x16_bf16 v[82:97], v[8:11], v[138:141], v[82:97]
	s_waitcnt lgkmcnt(9)
	v_mfma_f32_32x32x16_bf16 v[82:97], v[12:15], v[134:137], v[82:97]
	s_waitcnt lgkmcnt(8)
	v_mfma_f32_32x32x16_bf16 v[82:97], v[146:149], v[130:133], v[82:97]
	s_waitcnt lgkmcnt(7)
	v_mfma_f32_32x32x16_bf16 v[82:97], v[150:153], v[126:129], v[82:97]
	s_waitcnt lgkmcnt(6)
	v_mfma_f32_32x32x16_bf16 v[82:97], v[162:165], v[122:125], v[82:97]
	s_waitcnt lgkmcnt(5)
	v_mfma_f32_32x32x16_bf16 v[82:97], v[166:169], v[118:121], v[82:97]
	s_waitcnt lgkmcnt(4)
	v_mfma_f32_32x32x16_bf16 v[82:97], v[178:181], v[114:117], v[82:97]
	s_waitcnt lgkmcnt(3)
	v_mfma_f32_32x32x16_bf16 v[82:97], v[182:185], v[110:113], v[82:97]
	s_waitcnt lgkmcnt(2)
	v_mfma_f32_32x32x16_bf16 v[82:97], v[186:189], v[106:109], v[82:97]
	s_waitcnt lgkmcnt(1)
	v_mfma_f32_32x32x16_bf16 v[82:97], v[190:193], v[102:105], v[82:97]
	s_waitcnt lgkmcnt(0)
	v_mfma_f32_32x32x16_bf16 v[82:97], v[194:197], v[98:101], v[82:97]
	s_nop 11
	v_max_f32_e32 v1, v83, v83
	v_max_f32_e32 v2, v82, v82
	v_max_f32_e32 v1, v2, v1
	v_max3_f32 v1, v1, v84, v85
	v_max3_f32 v1, v1, v86, v87
	v_max3_f32 v1, v1, v88, v89
	v_max3_f32 v1, v1, v90, v91
	v_max3_f32 v1, v1, v92, v93
	v_max3_f32 v1, v1, v94, v95
	v_max3_f32 v1, v1, v96, v97
	v_mul_f32_e32 v1, 0x3dd53b94, v1
	v_mov_b32_e32 v2, v1
	s_nop 1
	v_permlane32_swap_b32_e32 v1, v2
	v_max_f32_e32 v2, v2, v2
	v_max_f32_e32 v1, v1, v1
	v_max_f32_e32 v1, v1, v2
	v_sub_f32_e32 v2, v1, v173
	v_cmp_ge_f32_e32 vcc, s12, v2
	s_cmp_eq_u64 vcc, exec
	s_cbranch_scc1 .LBB0_965
	v_max_f32_e32 v1, v1, v1
	v_max_f32_e32 v2, v173, v173
	v_max_f32_e32 v1, v2, v1
	v_sub_f32_e32 v2, v173, v1
	v_exp_f32_e32 v2, v2
	v_mov_b32_e32 v173, v1
	v_pk_mul_f32 v[80:81], v[80:81], v[2:3] op_sel_hi:[1,0]
	v_pk_mul_f32 v[78:79], v[78:79], v[2:3] op_sel_hi:[1,0]
	v_pk_mul_f32 v[76:77], v[76:77], v[2:3] op_sel_hi:[1,0]
	v_pk_mul_f32 v[74:75], v[74:75], v[2:3] op_sel_hi:[1,0]
	v_pk_mul_f32 v[72:73], v[72:73], v[2:3] op_sel_hi:[1,0]
	v_pk_mul_f32 v[70:71], v[70:71], v[2:3] op_sel_hi:[1,0]
	v_pk_mul_f32 v[68:69], v[68:69], v[2:3] op_sel_hi:[1,0]
	v_pk_mul_f32 v[66:67], v[66:67], v[2:3] op_sel_hi:[1,0]
	v_pk_mul_f32 v[48:49], v[48:49], v[2:3] op_sel_hi:[1,0]
	v_pk_mul_f32 v[46:47], v[46:47], v[2:3] op_sel_hi:[1,0]
	v_pk_mul_f32 v[44:45], v[44:45], v[2:3] op_sel_hi:[1,0]
	v_pk_mul_f32 v[42:43], v[42:43], v[2:3] op_sel_hi:[1,0]
	v_pk_mul_f32 v[40:41], v[40:41], v[2:3] op_sel_hi:[1,0]
	v_pk_mul_f32 v[38:39], v[38:39], v[2:3] op_sel_hi:[1,0]
	v_pk_mul_f32 v[36:37], v[36:37], v[2:3] op_sel_hi:[1,0]
	v_pk_mul_f32 v[34:35], v[34:35], v[2:3] op_sel_hi:[1,0]
	v_pk_mul_f32 v[64:65], v[64:65], v[2:3] op_sel_hi:[1,0]
	v_pk_mul_f32 v[62:63], v[62:63], v[2:3] op_sel_hi:[1,0]
	v_pk_mul_f32 v[60:61], v[60:61], v[2:3] op_sel_hi:[1,0]
	v_pk_mul_f32 v[58:59], v[58:59], v[2:3] op_sel_hi:[1,0]
	v_pk_mul_f32 v[56:57], v[56:57], v[2:3] op_sel_hi:[1,0]
	v_pk_mul_f32 v[54:55], v[54:55], v[2:3] op_sel_hi:[1,0]
	v_pk_mul_f32 v[52:53], v[52:53], v[2:3] op_sel_hi:[1,0]
	v_pk_mul_f32 v[50:51], v[50:51], v[2:3] op_sel_hi:[1,0]
	v_pk_mul_f32 v[32:33], v[32:33], v[2:3] op_sel_hi:[1,0]
	v_pk_mul_f32 v[30:31], v[30:31], v[2:3] op_sel_hi:[1,0]
	v_pk_mul_f32 v[28:29], v[28:29], v[2:3] op_sel_hi:[1,0]
	v_pk_mul_f32 v[26:27], v[26:27], v[2:3] op_sel_hi:[1,0]
	v_pk_mul_f32 v[24:25], v[24:25], v[2:3] op_sel_hi:[1,0]
	v_pk_mul_f32 v[22:23], v[22:23], v[2:3] op_sel_hi:[1,0]
	v_pk_mul_f32 v[20:21], v[20:21], v[2:3] op_sel_hi:[1,0]
	v_pk_mul_f32 v[18:19], v[18:19], v[2:3] op_sel_hi:[1,0]
	v_mul_f32_e32 v171, v171, v2

; __device__ __forceinline__ int opaque_tid() { int t = threadIdx.x; asm volatile("" : "+v"(t)); return t; }
; __device__ __forceinline__ void attn_odd_phase(const bf16_t* __restrict__ att, bf16_t* __restrict__ Ob, float* __restrict__ A12, unsigned* ctr) {
;     ...
;         if (opaque_tid() == 0) *slot = NBLK + (int)atomicAdd(ctr, 1u);
;         __syncthreads();
;         item = *slot;
.LBB0_971:
	s_or_b64 exec, exec, s[46:47]
	v_mov_b32_e32 v1, v0
	s_waitcnt lgkmcnt(0)
	s_nop 0
	v_cmp_eq_u32_e32 vcc, 0, v1
	s_and_saveexec_b64 s[12:13], vcc
	s_cbranch_execz .LBB0_938
	v_mov_b64_e32 v[4:5], s[48:49]
	s_mov_b64 s[14:15], src_shared_base
	s_add_i32 s14, 0, 0x23000
	s_cmp_lg_u32 s14, -1
	s_cselect_b32 s14, s14, 0
	s_cselect_b32 s15, s15, 0
	v_mov_b32_e32 v4, s14
	v_mov_b32_e32 v5, s15
	s_waitcnt vmcnt(0) lgkmcnt(0)
	v_add_u32_e32 v1, 0x100, v250
	flat_store_dword v[4:5], v1 sc0 sc1
	s_waitcnt vmcnt(0)
	s_branch .LBB0_938

; __global__ void __launch_bounds__(NTHR, 2) fwd_kernel(Params p_unused) {
	.amdhsa_kernel _ZN12_GLOBAL__N_110fwd_kernelENS_6ParamsE
		.amdhsa_group_segment_fixed_size 0
		.amdhsa_private_segment_fixed_size 0
		.amdhsa_kernarg_size 192
		.amdhsa_user_sgpr_count 2
		.amdhsa_user_sgpr_dispatch_ptr 0
		.amdhsa_user_sgpr_queue_ptr 0
		.amdhsa_user_sgpr_kernarg_segment_ptr 1
		.amdhsa_user_sgpr_dispatch_id 0
		.amdhsa_user_sgpr_kernarg_preload_length 0
		.amdhsa_user_sgpr_kernarg_preload_offset 0
		.amdhsa_user_sgpr_private_segment_size 0
		.amdhsa_uses_dynamic_stack 0
		.amdhsa_enable_private_segment 0
		.amdhsa_system_sgpr_workgroup_id_x 1
		.amdhsa_system_sgpr_workgroup_id_y 0
		.amdhsa_system_sgpr_workgroup_id_z 0
		.amdhsa_system_sgpr_workgroup_info 0
		.amdhsa_system_vgpr_workitem_id 0
		.amdhsa_next_free_vgpr 256
		.amdhsa_next_free_sgpr 102
		.amdhsa_accum_offset 256
		.amdhsa_reserve_vcc 1
		.amdhsa_float_round_mode_32 0
		.amdhsa_float_round_mode_16_64 0
		.amdhsa_float_denorm_mode_32 3
		.amdhsa_float_denorm_mode_16_64 3
		.amdhsa_dx10_clamp 1
		.amdhsa_ieee_mode 1
		.amdhsa_fp16_overflow 0
		.amdhsa_tg_split 0
		.amdhsa_exception_fp_ieee_invalid_op 0
		.amdhsa_exception_fp_denorm_src 0
		.amdhsa_exception_fp_ieee_div_zero 0
		.amdhsa_exception_fp_ieee_overflow 0
		.amdhsa_exception_fp_ieee_underflow 0
		.amdhsa_exception_fp_ieee_inexact 0
		.amdhsa_exception_int_div_zero 0
	.end_amdhsa_kernel

; __global__ void __launch_bounds__(NTHR, 2) fwd_kernel(Params p_unused) {
amdhsa.kernels:
  - .agpr_count:     0
    .args:
      - .offset:         0
        .size:           192
        .value_kind:     by_value
    .group_segment_fixed_size: 0
    .kernarg_segment_align: 8
    .kernarg_segment_size: 192
    .language:       OpenCL C
    .language_version:
      - 2
      - 0
    .max_flat_workgroup_size: 512
    .name:           _ZN12_GLOBAL__N_110fwd_kernelENS_6ParamsE
    .private_segment_fixed_size: 0
    .sgpr_count:     108
    .sgpr_spill_count: 192
    .symbol:         _ZN12_GLOBAL__N_110fwd_kernelENS_6ParamsE.kd
    .uniform_work_group_size: 1
    .uses_dynamic_stack: false
    .vgpr_count:     256
    .vgpr_spill_count: 0
    .wavefront_size: 64
